# speedup vs baseline: 1.0005x; 1.0005x over previous
; __device__ __forceinline__ float bflo(unsigned u) { return __uint_as_float(u << 16); }
; __device__ __forceinline__ float bfhi(unsigned u) { return __uint_as_float(u & 0xffff0000u); }
; __device__ __forceinline__ void phase_peer_u(const Params& p, int layer, int xs, int wid0, int wstride, char* smraw) {
;     ...
;   auto issue_rows = [&](int tt, u32x4 (&q)[16], u32x2& xv) {
; #pragma unroll
;     for (int i = 0; i < 16; ++i) q[i] = *(const u32x4*)(Uq + (ni[i >> 2][i & 3] * 128u + joff));
;     xv = *(const u32x2*)((const char*)p.hb + ((unsigned)(2 * tt + par) * 2048u + (unsigned)(sl * 512 + l * 8)));
;   };
;   auto landed = [&](u32x4 (&q)[16], u32x2& xv) {
;     asm volatile("" : "+v"(q[0]), "+v"(q[1]), "+v"(q[2]), "+v"(q[3]), "+v"(q[4]), "+v"(q[5]), "+v"(q[6]), "+v"(q[7]));
;     asm volatile("" : "+v"(q[8]), "+v"(q[9]), "+v"(q[10]), "+v"(q[11]), "+v"(q[12]), "+v"(q[13]), "+v"(q[14]), "+v"(q[15]));
;     asm volatile("" : "+v"(xv), "+v"(ni[0]), "+v"(ni[1]), "+v"(ni[2]), "+v"(ni[3]));
;   };
;   auto fence = [&]() { asm volatile("" ::: "memory"); };
;   auto compute = [&](int tt, const u32x4 (&q)[16], const u32x2& xv) {
;     const int t = 2 * tt + par;
;     int xq[8]; float sx; int sumx = 0;
;     {
;       const float x0 = bflo(xv[0]), x1 = bfhi(xv[0]), x2 = bflo(xv[1]), x3 = bfhi(xv[1]);
;       float mx = fmaxf(fmaxf(fabsf(x0), fabsf(x1)), fmaxf(fabsf(x2), fabsf(x3)));
; #pragma unroll
;       for (int m = 32; m >= 1; m >>= 1) mx = fmaxf(mx, __shfl_xor(mx, m));
;       const float inv = mx > 0.f ? 127.f / mx : 0.f;
;       sx = mx * (1.f / 127.f);
;       const int q0 = __float2int_rn(x0 * inv), q1 = __float2int_rn(x1 * inv), q2 = __float2int_rn(x2 * inv), q3 = __float2int_rn(x3 * inv);
;       asm volatile("" ::: "memory");
;       *(int*)(xqs + l * 4) = (q0 & 0xff) | ((q1 & 0xff) << 8) | ((q2 & 0xff) << 16) | ((q3 & 0xff) << 24);
;       asm volatile("" ::: "memory");
;       __builtin_amdgcn_wave_barrier();
;       asm volatile("" ::: "memory");
;       const u32x4 xa = *(const u32x4*)(xqs + j * 32), xb = *(const u32x4*)(xqs + j * 32 + 16);
;       asm volatile("" ::: "memory");
; #pragma unroll
;       for (int m = 0; m < 4; ++m) { xq[m] = (int)xa[m]; xq[4 + m] = (int)xb[m]; }
; #pragma unroll
;       for (int m = 0; m < 8; ++m) sumx = __builtin_amdgcn_sdot4(xq[m], 0x01010101, sumx, false);
.Lmy_pu0_bodyA:
	s_waitcnt vmcnt(20)
	s_mov_b32 s22, 4
	s_add_u32 s62, s60, s33
	s_cmp_ge_u32 s62, s61
	s_cbranch_scc1 .Lmy_pu0_noissueA
	v_lshl_add_u32 v86, v10, 7, v1
	v_lshl_add_u32 v87, v11, 7, v1
	v_lshl_add_u32 v88, v12, 7, v1
	v_lshl_add_u32 v89, v13, 7, v1
	v_lshl_add_u32 v90, v14, 7, v1
	v_lshl_add_u32 v91, v15, 7, v1
	v_lshl_add_u32 v92, v16, 7, v1
	v_lshl_add_u32 v93, v17, 7, v1
	v_lshl_add_u32 v94, v18, 7, v1
	v_lshl_add_u32 v95, v19, 7, v1
	v_lshl_add_u32 v96, v20, 7, v1
	v_lshl_add_u32 v97, v21, 7, v1
	v_lshl_add_u32 v98, v22, 7, v1
	v_lshl_add_u32 v99, v23, 7, v1
	v_lshl_add_u32 v100, v24, 7, v1
	v_lshl_add_u32 v101, v25, 7, v1
	s_mov_b32 s22, 21
	s_add_u32 s63, s62, s33
	s_cmp_ge_u32 s63, s61
	s_cbranch_scc1 .Lmy_pu0_noniA
	s_lshl_b32 s70, s63, 10
	v_add_u32_e32 v9, s70, v2
	global_load_dwordx4 v[10:13], v9, s[52:53]
	global_load_dwordx4 v[14:17], v9, s[52:53] offset:16
	global_load_dwordx4 v[18:21], v9, s[52:53] offset:32
	global_load_dwordx4 v[22:25], v9, s[52:53] offset:48
	s_mov_b32 s22, 25
.Lmy_pu0_noniA:
	s_lshl_b32 s70, s62, 1
	s_add_u32 s70, s70, s28
	s_lshl_b32 s70, s70, 11
	s_add_u32 s70, s70, s68
	v_add_u32_e32 v8, s70, v0
	global_load_dwordx2 v[28:29], v8, s[76:77]
	global_load_dwordx4 v[170:173], v86, s[66:67]
	global_load_dwordx4 v[174:177], v87, s[66:67]
	global_load_dwordx4 v[178:181], v88, s[66:67]
	global_load_dwordx4 v[182:185], v89, s[66:67]
	global_load_dwordx4 v[192:195], v90, s[66:67]
	global_load_dwordx4 v[196:199], v91, s[66:67]
	global_load_dwordx4 v[200:203], v92, s[66:67]
	global_load_dwordx4 v[204:207], v93, s[66:67]
	global_load_dwordx4 v[208:211], v94, s[66:67]
	global_load_dwordx4 v[212:215], v95, s[66:67]
	global_load_dwordx4 v[216:219], v96, s[66:67]
	global_load_dwordx4 v[220:223], v97, s[66:67]
	global_load_dwordx4 v[224:227], v98, s[66:67]
	global_load_dwordx4 v[228:231], v99, s[66:67]
	global_load_dwordx4 v[232:235], v100, s[66:67]
	global_load_dwordx4 v[236:239], v101, s[66:67]
.Lmy_pu0_noissueA:
	v_lshlrev_b32_e32 v40, 16, v26
	v_and_b32_e32 v41, 0xffff0000, v26
	v_lshlrev_b32_e32 v42, 16, v27
	v_and_b32_e32 v43, 0xffff0000, v27
	v_max_f32_e64 v44, |v40|, |v41|
	v_max3_f32 v44, |v42|, |v43|, v44
	s_nop 1
	v_max_f32_dpp v44, v44, v44 quad_perm:[1,0,3,2] row_mask:0xf bank_mask:0xf bound_ctrl:1
	s_nop 1
	v_max_f32_dpp v44, v44, v44 quad_perm:[2,3,0,1] row_mask:0xf bank_mask:0xf bound_ctrl:1
	s_nop 1
	v_max_f32_dpp v44, v44, v44 row_half_mirror row_mask:0xf bank_mask:0xf bound_ctrl:1
	s_nop 1
	v_max_f32_dpp v44, v44, v44 row_mirror row_mask:0xf bank_mask:0xf bound_ctrl:1
	s_nop 0
	v_readlane_b32 s6, v44, 0
	v_readlane_b32 s7, v44, 16
	v_readlane_b32 s10, v44, 32
	v_readlane_b32 s11, v44, 48
	s_nop 1
	v_mov_b32_e32 v45, s6
	v_max_f32_e32 v45, s7, v45
	v_max_f32_e32 v45, s10, v45
	v_max_f32_e32 v45, s11, v45
	v_div_scale_f32 v46, s[18:19], v45, v45, s69
	v_rcp_f32_e32 v47, v46
	s_nop 0
	v_fma_f32 v48, -v46, v47, 1.0
	v_fmac_f32_e32 v47, v48, v47
	v_div_scale_f32 v48, vcc, s69, v45, s69
	v_mul_f32_e32 v49, v48, v47
	v_fma_f32 v50, -v46, v49, v48
	v_fmac_f32_e32 v49, v50, v47
	v_fma_f32 v46, -v46, v49, v48
	v_div_fmas_f32 v46, v46, v47, v49
	v_div_fixup_f32 v46, v46, v45, s69
	v_cmp_lt_f32_e32 vcc, 0, v45
	v_mul_f32_e32 v52, 0x3c010204, v45
	v_mov_b32_e32 v84, 0
	v_cndmask_b32_e32 v46, 0, v46, vcc
	v_mul_f32_e32 v40, v46, v40
	v_mul_f32_e32 v41, v46, v41
	v_mul_f32_e32 v42, v46, v42
	v_mul_f32_e32 v43, v46, v43
	v_rndne_f32_e32 v40, v40
	v_rndne_f32_e32 v41, v41
	v_rndne_f32_e32 v42, v42
	v_rndne_f32_e32 v43, v43
	v_cvt_i32_f32_e32 v40, v40
	v_cvt_i32_f32_e32 v41, v41
	v_cvt_i32_f32_e32 v42, v42
	v_cvt_i32_f32_e32 v43, v43
	v_and_b32_e32 v40, 0xff, v40
	v_and_b32_e32 v41, 0xff, v41
	v_and_b32_e32 v42, 0xff, v42
	v_lshl_or_b32 v40, v41, 8, v40
	v_lshl_or_b32 v40, v42, 16, v40
	v_lshl_or_b32 v40, v43, 24, v40
	ds_write_b32 v3, v40
	ds_read_b128 v[32:35], v4
	ds_read_b128 v[36:39], v4 offset:16
	s_waitcnt lgkmcnt(0)
	v_dot4c_i32_i8_e32 v84, 0x1010101, v32
	v_dot4c_i32_i8_e32 v84, 0x1010101, v33
	v_dot4c_i32_i8_e32 v84, 0x1010101, v34
	v_dot4c_i32_i8_e32 v84, 0x1010101, v35
	v_dot4c_i32_i8_e32 v84, 0x1010101, v36
	v_dot4c_i32_i8_e32 v84, 0x1010101, v37
	v_dot4c_i32_i8_e32 v84, 0x1010101, v38
	v_dot4c_i32_i8_e32 v84, 0x1010101, v39
	s_cmp_eq_u32 s22, 25
	s_cbranch_scc1 .Lmy_pu0_w25A
	s_cmp_eq_u32 s22, 21
	s_cbranch_scc1 .Lmy_pu0_w21A
	s_waitcnt vmcnt(4)
	s_branch .Lmy_pu0_goA
.Lmy_pu0_w21A:
	s_waitcnt vmcnt(21)
	s_branch .Lmy_pu0_goA
.Lmy_pu0_w25A:
	s_waitcnt vmcnt(25)
; __device__ __forceinline__ void phase_peer_u(const Params& p, int layer, int xs, int wid0, int wstride, char* smraw) {
;     ...
; #pragma unroll
;     for (int i = 0; i < 16; ++i) {
;       int a = 0;
; #pragma unroll
;       for (int m = 0; m < 4; ++m) {
;         const unsigned dw = q[i][m];
;         a = __builtin_amdgcn_sdot4((int)(dw & 0x0f0f0f0fu), xq[2 * m], a, false);
;         a = __builtin_amdgcn_sdot4((int)((dw >> 4) & 0x0f0f0f0fu), xq[2 * m + 1], a, false);
;       }
;       a -= corr;
;       a += __builtin_amdgcn_update_dpp(0, a, 0xB1, 0xF, 0xF, true);
;       a += __builtin_amdgcn_update_dpp(0, a, 0x4E, 0xF, 0xF, true);
;       a += __builtin_amdgcn_update_dpp(0, a, 0x141, 0xF, 0xF, true);
;       pr[i] = (float)a * sx;
;     }
.Lmy_pu0_goA:
	v_and_b32_e32 v56, s21, v106
	v_lshrrev_b32_e32 v57, 4, v106
	v_and_b32_e32 v57, s21, v57
	v_and_b32_e32 v58, s21, v110
	v_lshrrev_b32_e32 v59, 4, v110
	v_and_b32_e32 v59, s21, v59
	v_and_b32_e32 v60, s21, v114
	v_lshrrev_b32_e32 v61, 4, v114
	v_and_b32_e32 v61, s21, v61
	v_and_b32_e32 v62, s21, v118
	v_lshrrev_b32_e32 v63, 4, v118
	v_and_b32_e32 v63, s21, v63
	v_mul_i32_i24_e32 v85, -8, v84
	v_mov_b32_e32 v64, v85
	v_mov_b32_e32 v65, v85
	v_mov_b32_e32 v66, v85
	v_mov_b32_e32 v67, v85
	v_dot4c_i32_i8_e32 v64, v56, v32
	v_dot4c_i32_i8_e32 v64, v57, v33
	v_dot4c_i32_i8_e32 v65, v58, v32
	v_dot4c_i32_i8_e32 v65, v59, v33
	v_dot4c_i32_i8_e32 v66, v60, v32
	v_dot4c_i32_i8_e32 v66, v61, v33
	v_dot4c_i32_i8_e32 v67, v62, v32
	v_dot4c_i32_i8_e32 v67, v63, v33
	v_and_b32_e32 v56, s21, v107
	v_lshrrev_b32_e32 v57, 4, v107
	v_and_b32_e32 v57, s21, v57
	v_and_b32_e32 v58, s21, v111
	v_lshrrev_b32_e32 v59, 4, v111
	v_and_b32_e32 v59, s21, v59
	v_and_b32_e32 v60, s21, v115
	v_lshrrev_b32_e32 v61, 4, v115
	v_and_b32_e32 v61, s21, v61
	v_and_b32_e32 v62, s21, v119
	v_lshrrev_b32_e32 v63, 4, v119
	v_and_b32_e32 v63, s21, v63
	v_dot4c_i32_i8_e32 v64, v56, v34
	v_dot4c_i32_i8_e32 v64, v57, v35
	v_dot4c_i32_i8_e32 v65, v58, v34
	v_dot4c_i32_i8_e32 v65, v59, v35
	v_dot4c_i32_i8_e32 v66, v60, v34
	v_dot4c_i32_i8_e32 v66, v61, v35
	v_dot4c_i32_i8_e32 v67, v62, v34
	v_dot4c_i32_i8_e32 v67, v63, v35
	v_and_b32_e32 v56, s21, v108
	v_lshrrev_b32_e32 v57, 4, v108
	v_and_b32_e32 v57, s21, v57
	v_and_b32_e32 v58, s21, v112
	v_lshrrev_b32_e32 v59, 4, v112
	v_and_b32_e32 v59, s21, v59
	v_and_b32_e32 v60, s21, v116
	v_lshrrev_b32_e32 v61, 4, v116
	v_and_b32_e32 v61, s21, v61
	v_and_b32_e32 v62, s21, v120
	v_lshrrev_b32_e32 v63, 4, v120
	v_and_b32_e32 v63, s21, v63
	v_dot4c_i32_i8_e32 v64, v56, v36
	v_dot4c_i32_i8_e32 v64, v57, v37
	v_dot4c_i32_i8_e32 v65, v58, v36
	v_dot4c_i32_i8_e32 v65, v59, v37
	v_dot4c_i32_i8_e32 v66, v60, v36
	v_dot4c_i32_i8_e32 v66, v61, v37
	v_dot4c_i32_i8_e32 v67, v62, v36
	v_dot4c_i32_i8_e32 v67, v63, v37
	v_and_b32_e32 v56, s21, v109
	v_lshrrev_b32_e32 v57, 4, v109
	v_and_b32_e32 v57, s21, v57
	v_and_b32_e32 v58, s21, v113
	v_lshrrev_b32_e32 v59, 4, v113
	v_and_b32_e32 v59, s21, v59
	v_and_b32_e32 v60, s21, v117
	v_lshrrev_b32_e32 v61, 4, v117
	v_and_b32_e32 v61, s21, v61
	v_and_b32_e32 v62, s21, v121
	v_lshrrev_b32_e32 v63, 4, v121
	v_and_b32_e32 v63, s21, v63
	v_dot4c_i32_i8_e32 v64, v56, v38
	v_dot4c_i32_i8_e32 v64, v57, v39
	v_dot4c_i32_i8_e32 v65, v58, v38
	v_dot4c_i32_i8_e32 v65, v59, v39
	v_dot4c_i32_i8_e32 v66, v60, v38
	v_dot4c_i32_i8_e32 v66, v61, v39
	v_dot4c_i32_i8_e32 v67, v62, v38
	v_dot4c_i32_i8_e32 v67, v63, v39
	v_add_u32_dpp v64, v64, v64 quad_perm:[1,0,3,2] row_mask:0xf bank_mask:0xf bound_ctrl:1
	v_add_u32_dpp v65, v65, v65 quad_perm:[1,0,3,2] row_mask:0xf bank_mask:0xf bound_ctrl:1
	v_add_u32_dpp v66, v66, v66 quad_perm:[1,0,3,2] row_mask:0xf bank_mask:0xf bound_ctrl:1
	v_add_u32_dpp v67, v67, v67 quad_perm:[1,0,3,2] row_mask:0xf bank_mask:0xf bound_ctrl:1
	v_add_u32_dpp v64, v64, v64 quad_perm:[2,3,0,1] row_mask:0xf bank_mask:0xf bound_ctrl:1
	v_add_u32_dpp v65, v65, v65 quad_perm:[2,3,0,1] row_mask:0xf bank_mask:0xf bound_ctrl:1
	v_add_u32_dpp v66, v66, v66 quad_perm:[2,3,0,1] row_mask:0xf bank_mask:0xf bound_ctrl:1
	v_add_u32_dpp v67, v67, v67 quad_perm:[2,3,0,1] row_mask:0xf bank_mask:0xf bound_ctrl:1
	v_add_u32_dpp v64, v64, v64 row_half_mirror row_mask:0xf bank_mask:0xf bound_ctrl:1
	v_add_u32_dpp v65, v65, v65 row_half_mirror row_mask:0xf bank_mask:0xf bound_ctrl:1
	v_add_u32_dpp v66, v66, v66 row_half_mirror row_mask:0xf bank_mask:0xf bound_ctrl:1
	v_add_u32_dpp v67, v67, v67 row_half_mirror row_mask:0xf bank_mask:0xf bound_ctrl:1
	v_cvt_f32_i32_e32 v68, v64
	v_cvt_f32_i32_e32 v69, v65
	v_cvt_f32_i32_e32 v70, v66
	v_cvt_f32_i32_e32 v71, v67
	v_pk_mul_f32 v[68:69], v[52:53], v[68:69] op_sel_hi:[0,1]
	v_pk_mul_f32 v[70:71], v[52:53], v[70:71] op_sel_hi:[0,1]
	v_and_b32_e32 v56, s21, v122
	v_lshrrev_b32_e32 v57, 4, v122
	v_and_b32_e32 v57, s21, v57
	v_and_b32_e32 v58, s21, v126
	v_lshrrev_b32_e32 v59, 4, v126
	v_and_b32_e32 v59, s21, v59
	v_and_b32_e32 v60, s21, v130
	v_lshrrev_b32_e32 v61, 4, v130
	v_and_b32_e32 v61, s21, v61
	v_and_b32_e32 v62, s21, v134
	v_lshrrev_b32_e32 v63, 4, v134
	v_and_b32_e32 v63, s21, v63
	v_mov_b32_e32 v64, v85
	v_mov_b32_e32 v65, v85
	v_mov_b32_e32 v66, v85
	v_mov_b32_e32 v67, v85
	v_dot4c_i32_i8_e32 v64, v56, v32
	v_dot4c_i32_i8_e32 v64, v57, v33
	v_dot4c_i32_i8_e32 v65, v58, v32
	v_dot4c_i32_i8_e32 v65, v59, v33
	v_dot4c_i32_i8_e32 v66, v60, v32
	v_dot4c_i32_i8_e32 v66, v61, v33
	v_dot4c_i32_i8_e32 v67, v62, v32
	v_dot4c_i32_i8_e32 v67, v63, v33
	v_and_b32_e32 v56, s21, v123
	v_lshrrev_b32_e32 v57, 4, v123
	v_and_b32_e32 v57, s21, v57
	v_and_b32_e32 v58, s21, v127
	v_lshrrev_b32_e32 v59, 4, v127
	v_and_b32_e32 v59, s21, v59
	v_and_b32_e32 v60, s21, v131
	v_lshrrev_b32_e32 v61, 4, v131
	v_and_b32_e32 v61, s21, v61
	v_and_b32_e32 v62, s21, v135
	v_lshrrev_b32_e32 v63, 4, v135
	v_and_b32_e32 v63, s21, v63
	v_dot4c_i32_i8_e32 v64, v56, v34
	v_dot4c_i32_i8_e32 v64, v57, v35
	v_dot4c_i32_i8_e32 v65, v58, v34
	v_dot4c_i32_i8_e32 v65, v59, v35
	v_dot4c_i32_i8_e32 v66, v60, v34
	v_dot4c_i32_i8_e32 v66, v61, v35
	v_dot4c_i32_i8_e32 v67, v62, v34
	v_dot4c_i32_i8_e32 v67, v63, v35
	v_and_b32_e32 v56, s21, v124
	v_lshrrev_b32_e32 v57, 4, v124
	v_and_b32_e32 v57, s21, v57
	v_and_b32_e32 v58, s21, v128
	v_lshrrev_b32_e32 v59, 4, v128
	v_and_b32_e32 v59, s21, v59
	v_and_b32_e32 v60, s21, v132
	v_lshrrev_b32_e32 v61, 4, v132
	v_and_b32_e32 v61, s21, v61
	v_and_b32_e32 v62, s21, v136
; __device__ __forceinline__ void phase_peer_u(const Params& p, int layer, int xs, int wid0, int wstride, char* smraw) {
;     ...
; #pragma unroll
;     for (int i = 0; i < 16; ++i) {
;       int a = 0;
; #pragma unroll
;       for (int m = 0; m < 4; ++m) {
;         const unsigned dw = q[i][m];
;         a = __builtin_amdgcn_sdot4((int)(dw & 0x0f0f0f0fu), xq[2 * m], a, false);
;         a = __builtin_amdgcn_sdot4((int)((dw >> 4) & 0x0f0f0f0fu), xq[2 * m + 1], a, false);
;       }
;       a -= corr;
;       a += __builtin_amdgcn_update_dpp(0, a, 0xB1, 0xF, 0xF, true);
;       a += __builtin_amdgcn_update_dpp(0, a, 0x4E, 0xF, 0xF, true);
;       a += __builtin_amdgcn_update_dpp(0, a, 0x141, 0xF, 0xF, true);
;       pr[i] = (float)a * sx;
;     }
	v_lshrrev_b32_e32 v63, 4, v136
	v_and_b32_e32 v63, s21, v63
	v_dot4c_i32_i8_e32 v64, v56, v36
	v_dot4c_i32_i8_e32 v64, v57, v37
	v_dot4c_i32_i8_e32 v65, v58, v36
	v_dot4c_i32_i8_e32 v65, v59, v37
	v_dot4c_i32_i8_e32 v66, v60, v36
	v_dot4c_i32_i8_e32 v66, v61, v37
	v_dot4c_i32_i8_e32 v67, v62, v36
	v_dot4c_i32_i8_e32 v67, v63, v37
	v_and_b32_e32 v56, s21, v125
	v_lshrrev_b32_e32 v57, 4, v125
	v_and_b32_e32 v57, s21, v57
	v_and_b32_e32 v58, s21, v129
	v_lshrrev_b32_e32 v59, 4, v129
	v_and_b32_e32 v59, s21, v59
	v_and_b32_e32 v60, s21, v133
	v_lshrrev_b32_e32 v61, 4, v133
	v_and_b32_e32 v61, s21, v61
	v_and_b32_e32 v62, s21, v137
	v_lshrrev_b32_e32 v63, 4, v137
	v_and_b32_e32 v63, s21, v63
	v_dot4c_i32_i8_e32 v64, v56, v38
	v_dot4c_i32_i8_e32 v64, v57, v39
	v_dot4c_i32_i8_e32 v65, v58, v38
	v_dot4c_i32_i8_e32 v65, v59, v39
	v_dot4c_i32_i8_e32 v66, v60, v38
	v_dot4c_i32_i8_e32 v66, v61, v39
	v_dot4c_i32_i8_e32 v67, v62, v38
	v_dot4c_i32_i8_e32 v67, v63, v39
	v_add_u32_dpp v64, v64, v64 quad_perm:[1,0,3,2] row_mask:0xf bank_mask:0xf bound_ctrl:1
	v_add_u32_dpp v65, v65, v65 quad_perm:[1,0,3,2] row_mask:0xf bank_mask:0xf bound_ctrl:1
	v_add_u32_dpp v66, v66, v66 quad_perm:[1,0,3,2] row_mask:0xf bank_mask:0xf bound_ctrl:1
	v_add_u32_dpp v67, v67, v67 quad_perm:[1,0,3,2] row_mask:0xf bank_mask:0xf bound_ctrl:1
	v_add_u32_dpp v64, v64, v64 quad_perm:[2,3,0,1] row_mask:0xf bank_mask:0xf bound_ctrl:1
	v_add_u32_dpp v65, v65, v65 quad_perm:[2,3,0,1] row_mask:0xf bank_mask:0xf bound_ctrl:1
	v_add_u32_dpp v66, v66, v66 quad_perm:[2,3,0,1] row_mask:0xf bank_mask:0xf bound_ctrl:1
	v_add_u32_dpp v67, v67, v67 quad_perm:[2,3,0,1] row_mask:0xf bank_mask:0xf bound_ctrl:1
	v_add_u32_dpp v64, v64, v64 row_half_mirror row_mask:0xf bank_mask:0xf bound_ctrl:1
	v_add_u32_dpp v65, v65, v65 row_half_mirror row_mask:0xf bank_mask:0xf bound_ctrl:1
	v_add_u32_dpp v66, v66, v66 row_half_mirror row_mask:0xf bank_mask:0xf bound_ctrl:1
	v_add_u32_dpp v67, v67, v67 row_half_mirror row_mask:0xf bank_mask:0xf bound_ctrl:1
	v_cvt_f32_i32_e32 v72, v64
	v_cvt_f32_i32_e32 v73, v65
	v_cvt_f32_i32_e32 v74, v66
	v_cvt_f32_i32_e32 v75, v67
	v_pk_mul_f32 v[72:73], v[52:53], v[72:73] op_sel_hi:[0,1]
	v_pk_mul_f32 v[74:75], v[52:53], v[74:75] op_sel_hi:[0,1]
	v_and_b32_e32 v56, s21, v138
	v_lshrrev_b32_e32 v57, 4, v138
	v_and_b32_e32 v57, s21, v57
	v_and_b32_e32 v58, s21, v142
	v_lshrrev_b32_e32 v59, 4, v142
	v_and_b32_e32 v59, s21, v59
	v_and_b32_e32 v60, s21, v146
	v_lshrrev_b32_e32 v61, 4, v146
	v_and_b32_e32 v61, s21, v61
	v_and_b32_e32 v62, s21, v150
	v_lshrrev_b32_e32 v63, 4, v150
	v_and_b32_e32 v63, s21, v63
	v_mov_b32_e32 v64, v85
	v_mov_b32_e32 v65, v85
	v_mov_b32_e32 v66, v85
	v_mov_b32_e32 v67, v85
	v_dot4c_i32_i8_e32 v64, v56, v32
	v_dot4c_i32_i8_e32 v64, v57, v33
	v_dot4c_i32_i8_e32 v65, v58, v32
	v_dot4c_i32_i8_e32 v65, v59, v33
	v_dot4c_i32_i8_e32 v66, v60, v32
	v_dot4c_i32_i8_e32 v66, v61, v33
	v_dot4c_i32_i8_e32 v67, v62, v32
	v_dot4c_i32_i8_e32 v67, v63, v33
	v_and_b32_e32 v56, s21, v139
	v_lshrrev_b32_e32 v57, 4, v139
	v_and_b32_e32 v57, s21, v57
	v_and_b32_e32 v58, s21, v143
	v_lshrrev_b32_e32 v59, 4, v143
	v_and_b32_e32 v59, s21, v59
	v_and_b32_e32 v60, s21, v147
	v_lshrrev_b32_e32 v61, 4, v147
	v_and_b32_e32 v61, s21, v61
	v_and_b32_e32 v62, s21, v151
	v_lshrrev_b32_e32 v63, 4, v151
	v_and_b32_e32 v63, s21, v63
	v_dot4c_i32_i8_e32 v64, v56, v34
	v_dot4c_i32_i8_e32 v64, v57, v35
	v_dot4c_i32_i8_e32 v65, v58, v34
	v_dot4c_i32_i8_e32 v65, v59, v35
	v_dot4c_i32_i8_e32 v66, v60, v34
	v_dot4c_i32_i8_e32 v66, v61, v35
	v_dot4c_i32_i8_e32 v67, v62, v34
	v_dot4c_i32_i8_e32 v67, v63, v35
	v_and_b32_e32 v56, s21, v140
	v_lshrrev_b32_e32 v57, 4, v140
	v_and_b32_e32 v57, s21, v57
	v_and_b32_e32 v58, s21, v144
	v_lshrrev_b32_e32 v59, 4, v144
	v_and_b32_e32 v59, s21, v59
	v_and_b32_e32 v60, s21, v148
	v_lshrrev_b32_e32 v61, 4, v148
	v_and_b32_e32 v61, s21, v61
	v_and_b32_e32 v62, s21, v152
	v_lshrrev_b32_e32 v63, 4, v152
	v_and_b32_e32 v63, s21, v63
	v_dot4c_i32_i8_e32 v64, v56, v36
	v_dot4c_i32_i8_e32 v64, v57, v37
	v_dot4c_i32_i8_e32 v65, v58, v36
	v_dot4c_i32_i8_e32 v65, v59, v37
	v_dot4c_i32_i8_e32 v66, v60, v36
	v_dot4c_i32_i8_e32 v66, v61, v37
	v_dot4c_i32_i8_e32 v67, v62, v36
	v_dot4c_i32_i8_e32 v67, v63, v37
	v_and_b32_e32 v56, s21, v141
	v_lshrrev_b32_e32 v57, 4, v141
	v_and_b32_e32 v57, s21, v57
	v_and_b32_e32 v58, s21, v145
	v_lshrrev_b32_e32 v59, 4, v145
	v_and_b32_e32 v59, s21, v59
	v_and_b32_e32 v60, s21, v149
	v_lshrrev_b32_e32 v61, 4, v149
	v_and_b32_e32 v61, s21, v61
	v_and_b32_e32 v62, s21, v153
	v_lshrrev_b32_e32 v63, 4, v153
	v_and_b32_e32 v63, s21, v63
	v_dot4c_i32_i8_e32 v64, v56, v38
	v_dot4c_i32_i8_e32 v64, v57, v39
	v_dot4c_i32_i8_e32 v65, v58, v38
	v_dot4c_i32_i8_e32 v65, v59, v39
	v_dot4c_i32_i8_e32 v66, v60, v38
	v_dot4c_i32_i8_e32 v66, v61, v39
	v_dot4c_i32_i8_e32 v67, v62, v38
	v_dot4c_i32_i8_e32 v67, v63, v39
	v_add_u32_dpp v64, v64, v64 quad_perm:[1,0,3,2] row_mask:0xf bank_mask:0xf bound_ctrl:1
	v_add_u32_dpp v65, v65, v65 quad_perm:[1,0,3,2] row_mask:0xf bank_mask:0xf bound_ctrl:1
	v_add_u32_dpp v66, v66, v66 quad_perm:[1,0,3,2] row_mask:0xf bank_mask:0xf bound_ctrl:1
	v_add_u32_dpp v67, v67, v67 quad_perm:[1,0,3,2] row_mask:0xf bank_mask:0xf bound_ctrl:1
	v_add_u32_dpp v64, v64, v64 quad_perm:[2,3,0,1] row_mask:0xf bank_mask:0xf bound_ctrl:1
; __device__ __forceinline__ void phase_peer_u(const Params& p, int layer, int xs, int wid0, int wstride, char* smraw) {
;     ...
; #pragma unroll
;     for (int i = 0; i < 16; ++i) {
;       int a = 0;
; #pragma unroll
;       for (int m = 0; m < 4; ++m) {
;         const unsigned dw = q[i][m];
;         a = __builtin_amdgcn_sdot4((int)(dw & 0x0f0f0f0fu), xq[2 * m], a, false);
;         a = __builtin_amdgcn_sdot4((int)((dw >> 4) & 0x0f0f0f0fu), xq[2 * m + 1], a, false);
;       }
;       a -= corr;
;       a += __builtin_amdgcn_update_dpp(0, a, 0xB1, 0xF, 0xF, true);
;       a += __builtin_amdgcn_update_dpp(0, a, 0x4E, 0xF, 0xF, true);
;       a += __builtin_amdgcn_update_dpp(0, a, 0x141, 0xF, 0xF, true);
;       pr[i] = (float)a * sx;
;     }
;     if (j == 0) {
;       f32x4* dst = (f32x4*)((char*)p.actp + ((unsigned)t * 4096u + (unsigned)(sl * 512 + g * 64)));
; #pragma unroll
;       for (int q4 = 0; q4 < 4; ++q4) dst[q4] = f32x4{pr[q4 * 4], pr[q4 * 4 + 1], pr[q4 * 4 + 2], pr[q4 * 4 + 3]};
;     }
	v_add_u32_dpp v65, v65, v65 quad_perm:[2,3,0,1] row_mask:0xf bank_mask:0xf bound_ctrl:1
	v_add_u32_dpp v66, v66, v66 quad_perm:[2,3,0,1] row_mask:0xf bank_mask:0xf bound_ctrl:1
	v_add_u32_dpp v67, v67, v67 quad_perm:[2,3,0,1] row_mask:0xf bank_mask:0xf bound_ctrl:1
	v_add_u32_dpp v64, v64, v64 row_half_mirror row_mask:0xf bank_mask:0xf bound_ctrl:1
	v_add_u32_dpp v65, v65, v65 row_half_mirror row_mask:0xf bank_mask:0xf bound_ctrl:1
	v_add_u32_dpp v66, v66, v66 row_half_mirror row_mask:0xf bank_mask:0xf bound_ctrl:1
	v_add_u32_dpp v67, v67, v67 row_half_mirror row_mask:0xf bank_mask:0xf bound_ctrl:1
	v_cvt_f32_i32_e32 v76, v64
	v_cvt_f32_i32_e32 v77, v65
	v_cvt_f32_i32_e32 v78, v66
	v_cvt_f32_i32_e32 v79, v67
	v_pk_mul_f32 v[76:77], v[52:53], v[76:77] op_sel_hi:[0,1]
	v_pk_mul_f32 v[78:79], v[52:53], v[78:79] op_sel_hi:[0,1]
	v_and_b32_e32 v56, s21, v154
	v_lshrrev_b32_e32 v57, 4, v154
	v_and_b32_e32 v57, s21, v57
	v_and_b32_e32 v58, s21, v158
	v_lshrrev_b32_e32 v59, 4, v158
	v_and_b32_e32 v59, s21, v59
	v_and_b32_e32 v60, s21, v162
	v_lshrrev_b32_e32 v61, 4, v162
	v_and_b32_e32 v61, s21, v61
	v_and_b32_e32 v62, s21, v166
	v_lshrrev_b32_e32 v63, 4, v166
	v_and_b32_e32 v63, s21, v63
	v_mov_b32_e32 v64, v85
	v_mov_b32_e32 v65, v85
	v_mov_b32_e32 v66, v85
	v_mov_b32_e32 v67, v85
	v_dot4c_i32_i8_e32 v64, v56, v32
	v_dot4c_i32_i8_e32 v64, v57, v33
	v_dot4c_i32_i8_e32 v65, v58, v32
	v_dot4c_i32_i8_e32 v65, v59, v33
	v_dot4c_i32_i8_e32 v66, v60, v32
	v_dot4c_i32_i8_e32 v66, v61, v33
	v_dot4c_i32_i8_e32 v67, v62, v32
	v_dot4c_i32_i8_e32 v67, v63, v33
	v_and_b32_e32 v56, s21, v155
	v_lshrrev_b32_e32 v57, 4, v155
	v_and_b32_e32 v57, s21, v57
	v_and_b32_e32 v58, s21, v159
	v_lshrrev_b32_e32 v59, 4, v159
	v_and_b32_e32 v59, s21, v59
	v_and_b32_e32 v60, s21, v163
	v_lshrrev_b32_e32 v61, 4, v163
	v_and_b32_e32 v61, s21, v61
	v_and_b32_e32 v62, s21, v167
	v_lshrrev_b32_e32 v63, 4, v167
	v_and_b32_e32 v63, s21, v63
	v_dot4c_i32_i8_e32 v64, v56, v34
	v_dot4c_i32_i8_e32 v64, v57, v35
	v_dot4c_i32_i8_e32 v65, v58, v34
	v_dot4c_i32_i8_e32 v65, v59, v35
	v_dot4c_i32_i8_e32 v66, v60, v34
	v_dot4c_i32_i8_e32 v66, v61, v35
	v_dot4c_i32_i8_e32 v67, v62, v34
	v_dot4c_i32_i8_e32 v67, v63, v35
	v_and_b32_e32 v56, s21, v156
	v_lshrrev_b32_e32 v57, 4, v156
	v_and_b32_e32 v57, s21, v57
	v_and_b32_e32 v58, s21, v160
	v_lshrrev_b32_e32 v59, 4, v160
	v_and_b32_e32 v59, s21, v59
	v_and_b32_e32 v60, s21, v164
	v_lshrrev_b32_e32 v61, 4, v164
	v_and_b32_e32 v61, s21, v61
	v_and_b32_e32 v62, s21, v168
	v_lshrrev_b32_e32 v63, 4, v168
	v_and_b32_e32 v63, s21, v63
	v_dot4c_i32_i8_e32 v64, v56, v36
	v_dot4c_i32_i8_e32 v64, v57, v37
	v_dot4c_i32_i8_e32 v65, v58, v36
	v_dot4c_i32_i8_e32 v65, v59, v37
	v_dot4c_i32_i8_e32 v66, v60, v36
	v_dot4c_i32_i8_e32 v66, v61, v37
	v_dot4c_i32_i8_e32 v67, v62, v36
	v_dot4c_i32_i8_e32 v67, v63, v37
	v_and_b32_e32 v56, s21, v157
	v_lshrrev_b32_e32 v57, 4, v157
	v_and_b32_e32 v57, s21, v57
	v_and_b32_e32 v58, s21, v161
	v_lshrrev_b32_e32 v59, 4, v161
	v_and_b32_e32 v59, s21, v59
	v_and_b32_e32 v60, s21, v165
	v_lshrrev_b32_e32 v61, 4, v165
	v_and_b32_e32 v61, s21, v61
	v_and_b32_e32 v62, s21, v169
	v_lshrrev_b32_e32 v63, 4, v169
	v_and_b32_e32 v63, s21, v63
	v_dot4c_i32_i8_e32 v64, v56, v38
	v_dot4c_i32_i8_e32 v64, v57, v39
	v_dot4c_i32_i8_e32 v65, v58, v38
	v_dot4c_i32_i8_e32 v65, v59, v39
	v_dot4c_i32_i8_e32 v66, v60, v38
	v_dot4c_i32_i8_e32 v66, v61, v39
	v_dot4c_i32_i8_e32 v67, v62, v38
	v_dot4c_i32_i8_e32 v67, v63, v39
	v_add_u32_dpp v64, v64, v64 quad_perm:[1,0,3,2] row_mask:0xf bank_mask:0xf bound_ctrl:1
	v_add_u32_dpp v65, v65, v65 quad_perm:[1,0,3,2] row_mask:0xf bank_mask:0xf bound_ctrl:1
	v_add_u32_dpp v66, v66, v66 quad_perm:[1,0,3,2] row_mask:0xf bank_mask:0xf bound_ctrl:1
	v_add_u32_dpp v67, v67, v67 quad_perm:[1,0,3,2] row_mask:0xf bank_mask:0xf bound_ctrl:1
	v_add_u32_dpp v64, v64, v64 quad_perm:[2,3,0,1] row_mask:0xf bank_mask:0xf bound_ctrl:1
	v_add_u32_dpp v65, v65, v65 quad_perm:[2,3,0,1] row_mask:0xf bank_mask:0xf bound_ctrl:1
	v_add_u32_dpp v66, v66, v66 quad_perm:[2,3,0,1] row_mask:0xf bank_mask:0xf bound_ctrl:1
	v_add_u32_dpp v67, v67, v67 quad_perm:[2,3,0,1] row_mask:0xf bank_mask:0xf bound_ctrl:1
	v_add_u32_dpp v64, v64, v64 row_half_mirror row_mask:0xf bank_mask:0xf bound_ctrl:1
	v_add_u32_dpp v65, v65, v65 row_half_mirror row_mask:0xf bank_mask:0xf bound_ctrl:1
	v_add_u32_dpp v66, v66, v66 row_half_mirror row_mask:0xf bank_mask:0xf bound_ctrl:1
	v_add_u32_dpp v67, v67, v67 row_half_mirror row_mask:0xf bank_mask:0xf bound_ctrl:1
	v_cvt_f32_i32_e32 v80, v64
	v_cvt_f32_i32_e32 v81, v65
	v_cvt_f32_i32_e32 v82, v66
	v_cvt_f32_i32_e32 v83, v67
	v_pk_mul_f32 v[80:81], v[52:53], v[80:81] op_sel_hi:[0,1]
	v_pk_mul_f32 v[82:83], v[52:53], v[82:83] op_sel_hi:[0,1]
	s_lshl_b32 s70, s60, 1
	s_add_u32 s70, s70, s28
	s_lshl_b32 s70, s70, 12
	s_add_u32 s70, s70, s68
	s_mov_b64 s[74:75], exec
	s_and_b64 exec, exec, s[72:73]
	v_add_u32_e32 v9, s70, v5
	global_store_dwordx4 v9, v[68:71], s[64:65]
	global_store_dwordx4 v9, v[72:75], s[64:65] offset:16
	global_store_dwordx4 v9, v[76:79], s[64:65] offset:32
	global_store_dwordx4 v9, v[80:83], s[64:65] offset:48
	s_mov_b64 exec, s[74:75]
	s_mov_b32 s60, s62
	s_cmp_lt_u32 s60, s61
	s_cbranch_scc0 .Lmy_pu0_done

; __device__ __forceinline__ float bflo(unsigned u) { return __uint_as_float(u << 16); }
; __device__ __forceinline__ float bfhi(unsigned u) { return __uint_as_float(u & 0xffff0000u); }
; __device__ __forceinline__ void phase_peer_u(const Params& p, int layer, int xs, int wid0, int wstride, char* smraw) {
;     ...
;   auto issue_rows = [&](int tt, u32x4 (&q)[16], u32x2& xv) {
; #pragma unroll
;     for (int i = 0; i < 16; ++i) q[i] = *(const u32x4*)(Uq + (ni[i >> 2][i & 3] * 128u + joff));
;     xv = *(const u32x2*)((const char*)p.hb + ((unsigned)(2 * tt + par) * 2048u + (unsigned)(sl * 512 + l * 8)));
;   };
;   auto landed = [&](u32x4 (&q)[16], u32x2& xv) {
;     asm volatile("" : "+v"(q[0]), "+v"(q[1]), "+v"(q[2]), "+v"(q[3]), "+v"(q[4]), "+v"(q[5]), "+v"(q[6]), "+v"(q[7]));
;     asm volatile("" : "+v"(q[8]), "+v"(q[9]), "+v"(q[10]), "+v"(q[11]), "+v"(q[12]), "+v"(q[13]), "+v"(q[14]), "+v"(q[15]));
;     asm volatile("" : "+v"(xv), "+v"(ni[0]), "+v"(ni[1]), "+v"(ni[2]), "+v"(ni[3]));
;   };
;   auto fence = [&]() { asm volatile("" ::: "memory"); };
;   auto compute = [&](int tt, const u32x4 (&q)[16], const u32x2& xv) {
;     const int t = 2 * tt + par;
;     int xq[8]; float sx; int sumx = 0;
;     {
;       const float x0 = bflo(xv[0]), x1 = bfhi(xv[0]), x2 = bflo(xv[1]), x3 = bfhi(xv[1]);
;       float mx = fmaxf(fmaxf(fabsf(x0), fabsf(x1)), fmaxf(fabsf(x2), fabsf(x3)));
; #pragma unroll
;       for (int m = 32; m >= 1; m >>= 1) mx = fmaxf(mx, __shfl_xor(mx, m));
;       const float inv = mx > 0.f ? 127.f / mx : 0.f;
;       sx = mx * (1.f / 127.f);
;       const int q0 = __float2int_rn(x0 * inv), q1 = __float2int_rn(x1 * inv), q2 = __float2int_rn(x2 * inv), q3 = __float2int_rn(x3 * inv);
;       asm volatile("" ::: "memory");
;       *(int*)(xqs + l * 4) = (q0 & 0xff) | ((q1 & 0xff) << 8) | ((q2 & 0xff) << 16) | ((q3 & 0xff) << 24);
;       asm volatile("" ::: "memory");
;       __builtin_amdgcn_wave_barrier();
;       asm volatile("" ::: "memory");
;       const u32x4 xa = *(const u32x4*)(xqs + j * 32), xb = *(const u32x4*)(xqs + j * 32 + 16);
;       asm volatile("" ::: "memory");
; #pragma unroll
;       for (int m = 0; m < 4; ++m) { xq[m] = (int)xa[m]; xq[4 + m] = (int)xb[m]; }
; #pragma unroll
;       for (int m = 0; m < 8; ++m) sumx = __builtin_amdgcn_sdot4(xq[m], 0x01010101, sumx, false);
.Lmy_pu0_noniB:
	s_lshl_b32 s70, s62, 1
	s_add_u32 s70, s70, s28
	s_lshl_b32 s70, s70, 11
	s_add_u32 s70, s70, s68
	v_add_u32_e32 v8, s70, v0
	global_load_dwordx2 v[26:27], v8, s[76:77]
	global_load_dwordx4 v[106:109], v86, s[66:67]
	global_load_dwordx4 v[110:113], v87, s[66:67]
	global_load_dwordx4 v[114:117], v88, s[66:67]
	global_load_dwordx4 v[118:121], v89, s[66:67]
	global_load_dwordx4 v[122:125], v90, s[66:67]
	global_load_dwordx4 v[126:129], v91, s[66:67]
	global_load_dwordx4 v[130:133], v92, s[66:67]
	global_load_dwordx4 v[134:137], v93, s[66:67]
	global_load_dwordx4 v[138:141], v94, s[66:67]
	global_load_dwordx4 v[142:145], v95, s[66:67]
	global_load_dwordx4 v[146:149], v96, s[66:67]
	global_load_dwordx4 v[150:153], v97, s[66:67]
	global_load_dwordx4 v[154:157], v98, s[66:67]
	global_load_dwordx4 v[158:161], v99, s[66:67]
	global_load_dwordx4 v[162:165], v100, s[66:67]
	global_load_dwordx4 v[166:169], v101, s[66:67]
.Lmy_pu0_noissueB:
	v_lshlrev_b32_e32 v40, 16, v28
	v_and_b32_e32 v41, 0xffff0000, v28
	v_lshlrev_b32_e32 v42, 16, v29
	v_and_b32_e32 v43, 0xffff0000, v29
	v_max_f32_e64 v44, |v40|, |v41|
	v_max3_f32 v44, |v42|, |v43|, v44
	s_nop 1
	v_max_f32_dpp v44, v44, v44 quad_perm:[1,0,3,2] row_mask:0xf bank_mask:0xf bound_ctrl:1
	s_nop 1
	v_max_f32_dpp v44, v44, v44 quad_perm:[2,3,0,1] row_mask:0xf bank_mask:0xf bound_ctrl:1
	s_nop 1
	v_max_f32_dpp v44, v44, v44 row_half_mirror row_mask:0xf bank_mask:0xf bound_ctrl:1
	s_nop 1
	v_max_f32_dpp v44, v44, v44 row_mirror row_mask:0xf bank_mask:0xf bound_ctrl:1
	s_nop 0
	v_readlane_b32 s6, v44, 0
	v_readlane_b32 s7, v44, 16
	v_readlane_b32 s10, v44, 32
	v_readlane_b32 s11, v44, 48
	s_nop 1
	v_mov_b32_e32 v45, s6
	v_max_f32_e32 v45, s7, v45
	v_max_f32_e32 v45, s10, v45
	v_max_f32_e32 v45, s11, v45
	v_div_scale_f32 v46, s[18:19], v45, v45, s69
	v_rcp_f32_e32 v47, v46
	s_nop 0
	v_fma_f32 v48, -v46, v47, 1.0
	v_fmac_f32_e32 v47, v48, v47
	v_div_scale_f32 v48, vcc, s69, v45, s69
	v_mul_f32_e32 v49, v48, v47
	v_fma_f32 v50, -v46, v49, v48
	v_fmac_f32_e32 v49, v50, v47
	v_fma_f32 v46, -v46, v49, v48
	v_div_fmas_f32 v46, v46, v47, v49
	v_div_fixup_f32 v46, v46, v45, s69
	v_cmp_lt_f32_e32 vcc, 0, v45
	v_mul_f32_e32 v52, 0x3c010204, v45
	v_mov_b32_e32 v84, 0
	v_cndmask_b32_e32 v46, 0, v46, vcc
	v_mul_f32_e32 v40, v46, v40
	v_mul_f32_e32 v41, v46, v41
	v_mul_f32_e32 v42, v46, v42
	v_mul_f32_e32 v43, v46, v43
	v_rndne_f32_e32 v40, v40
	v_rndne_f32_e32 v41, v41
	v_rndne_f32_e32 v42, v42
	v_rndne_f32_e32 v43, v43
	v_cvt_i32_f32_e32 v40, v40
	v_cvt_i32_f32_e32 v41, v41
	v_cvt_i32_f32_e32 v42, v42
	v_cvt_i32_f32_e32 v43, v43
	v_and_b32_e32 v40, 0xff, v40
	v_and_b32_e32 v41, 0xff, v41
	v_and_b32_e32 v42, 0xff, v42
	v_lshl_or_b32 v40, v41, 8, v40
	v_lshl_or_b32 v40, v42, 16, v40
	v_lshl_or_b32 v40, v43, 24, v40
	ds_write_b32 v3, v40
	ds_read_b128 v[32:35], v4
	ds_read_b128 v[36:39], v4 offset:16
	s_waitcnt lgkmcnt(0)
	v_dot4c_i32_i8_e32 v84, 0x1010101, v32
	v_dot4c_i32_i8_e32 v84, 0x1010101, v33
	v_dot4c_i32_i8_e32 v84, 0x1010101, v34
	v_dot4c_i32_i8_e32 v84, 0x1010101, v35
	v_dot4c_i32_i8_e32 v84, 0x1010101, v36
	v_dot4c_i32_i8_e32 v84, 0x1010101, v37
	v_dot4c_i32_i8_e32 v84, 0x1010101, v38
	v_dot4c_i32_i8_e32 v84, 0x1010101, v39
	s_cmp_eq_u32 s22, 25
	s_cbranch_scc1 .Lmy_pu0_w25B
	s_cmp_eq_u32 s22, 21
	s_cbranch_scc1 .Lmy_pu0_w21B
	s_waitcnt vmcnt(4)
	s_branch .Lmy_pu0_goB

; __device__ __forceinline__ void phase_peer_u(const Params& p, int layer, int xs, int wid0, int wstride, char* smraw) {
;     ...
; #pragma unroll
;     for (int i = 0; i < 16; ++i) {
;       int a = 0;
; #pragma unroll
;       for (int m = 0; m < 4; ++m) {
;         const unsigned dw = q[i][m];
;         a = __builtin_amdgcn_sdot4((int)(dw & 0x0f0f0f0fu), xq[2 * m], a, false);
;         a = __builtin_amdgcn_sdot4((int)((dw >> 4) & 0x0f0f0f0fu), xq[2 * m + 1], a, false);
;       }
;       a -= corr;
;       a += __builtin_amdgcn_update_dpp(0, a, 0xB1, 0xF, 0xF, true);
;       a += __builtin_amdgcn_update_dpp(0, a, 0x4E, 0xF, 0xF, true);
;       a += __builtin_amdgcn_update_dpp(0, a, 0x141, 0xF, 0xF, true);
;       pr[i] = (float)a * sx;
;     }
.Lmy_pu0_goB:
	v_and_b32_e32 v56, s21, v170
	v_lshrrev_b32_e32 v57, 4, v170
	v_and_b32_e32 v57, s21, v57
	v_and_b32_e32 v58, s21, v174
	v_lshrrev_b32_e32 v59, 4, v174
	v_and_b32_e32 v59, s21, v59
	v_and_b32_e32 v60, s21, v178
	v_lshrrev_b32_e32 v61, 4, v178
	v_and_b32_e32 v61, s21, v61
	v_and_b32_e32 v62, s21, v182
	v_lshrrev_b32_e32 v63, 4, v182
	v_and_b32_e32 v63, s21, v63
	v_mul_i32_i24_e32 v85, -8, v84
	v_mov_b32_e32 v64, v85
	v_mov_b32_e32 v65, v85
	v_mov_b32_e32 v66, v85
	v_mov_b32_e32 v67, v85
	v_dot4c_i32_i8_e32 v64, v56, v32
	v_dot4c_i32_i8_e32 v64, v57, v33
	v_dot4c_i32_i8_e32 v65, v58, v32
	v_dot4c_i32_i8_e32 v65, v59, v33
	v_dot4c_i32_i8_e32 v66, v60, v32
	v_dot4c_i32_i8_e32 v66, v61, v33
	v_dot4c_i32_i8_e32 v67, v62, v32
	v_dot4c_i32_i8_e32 v67, v63, v33
	v_and_b32_e32 v56, s21, v171
	v_lshrrev_b32_e32 v57, 4, v171
	v_and_b32_e32 v57, s21, v57
	v_and_b32_e32 v58, s21, v175
	v_lshrrev_b32_e32 v59, 4, v175
	v_and_b32_e32 v59, s21, v59
	v_and_b32_e32 v60, s21, v179
	v_lshrrev_b32_e32 v61, 4, v179
	v_and_b32_e32 v61, s21, v61
	v_and_b32_e32 v62, s21, v183
	v_lshrrev_b32_e32 v63, 4, v183
	v_and_b32_e32 v63, s21, v63
	v_dot4c_i32_i8_e32 v64, v56, v34
	v_dot4c_i32_i8_e32 v64, v57, v35
	v_dot4c_i32_i8_e32 v65, v58, v34
	v_dot4c_i32_i8_e32 v65, v59, v35
	v_dot4c_i32_i8_e32 v66, v60, v34
	v_dot4c_i32_i8_e32 v66, v61, v35
	v_dot4c_i32_i8_e32 v67, v62, v34
	v_dot4c_i32_i8_e32 v67, v63, v35
	v_and_b32_e32 v56, s21, v172
	v_lshrrev_b32_e32 v57, 4, v172
	v_and_b32_e32 v57, s21, v57
	v_and_b32_e32 v58, s21, v176
	v_lshrrev_b32_e32 v59, 4, v176
	v_and_b32_e32 v59, s21, v59
	v_and_b32_e32 v60, s21, v180
	v_lshrrev_b32_e32 v61, 4, v180
	v_and_b32_e32 v61, s21, v61
	v_and_b32_e32 v62, s21, v184
	v_lshrrev_b32_e32 v63, 4, v184
	v_and_b32_e32 v63, s21, v63
	v_dot4c_i32_i8_e32 v64, v56, v36
	v_dot4c_i32_i8_e32 v64, v57, v37
	v_dot4c_i32_i8_e32 v65, v58, v36
	v_dot4c_i32_i8_e32 v65, v59, v37
	v_dot4c_i32_i8_e32 v66, v60, v36
	v_dot4c_i32_i8_e32 v66, v61, v37
	v_dot4c_i32_i8_e32 v67, v62, v36
	v_dot4c_i32_i8_e32 v67, v63, v37
	v_and_b32_e32 v56, s21, v173
	v_lshrrev_b32_e32 v57, 4, v173
	v_and_b32_e32 v57, s21, v57
	v_and_b32_e32 v58, s21, v177
	v_lshrrev_b32_e32 v59, 4, v177
	v_and_b32_e32 v59, s21, v59
	v_and_b32_e32 v60, s21, v181
	v_lshrrev_b32_e32 v61, 4, v181
	v_and_b32_e32 v61, s21, v61
	v_and_b32_e32 v62, s21, v185
	v_lshrrev_b32_e32 v63, 4, v185
	v_and_b32_e32 v63, s21, v63
	v_dot4c_i32_i8_e32 v64, v56, v38
	v_dot4c_i32_i8_e32 v64, v57, v39
	v_dot4c_i32_i8_e32 v65, v58, v38
	v_dot4c_i32_i8_e32 v65, v59, v39
	v_dot4c_i32_i8_e32 v66, v60, v38
	v_dot4c_i32_i8_e32 v66, v61, v39
	v_dot4c_i32_i8_e32 v67, v62, v38
	v_dot4c_i32_i8_e32 v67, v63, v39
	v_add_u32_dpp v64, v64, v64 quad_perm:[1,0,3,2] row_mask:0xf bank_mask:0xf bound_ctrl:1
	v_add_u32_dpp v65, v65, v65 quad_perm:[1,0,3,2] row_mask:0xf bank_mask:0xf bound_ctrl:1
	v_add_u32_dpp v66, v66, v66 quad_perm:[1,0,3,2] row_mask:0xf bank_mask:0xf bound_ctrl:1
	v_add_u32_dpp v67, v67, v67 quad_perm:[1,0,3,2] row_mask:0xf bank_mask:0xf bound_ctrl:1
	v_add_u32_dpp v64, v64, v64 quad_perm:[2,3,0,1] row_mask:0xf bank_mask:0xf bound_ctrl:1
	v_add_u32_dpp v65, v65, v65 quad_perm:[2,3,0,1] row_mask:0xf bank_mask:0xf bound_ctrl:1
	v_add_u32_dpp v66, v66, v66 quad_perm:[2,3,0,1] row_mask:0xf bank_mask:0xf bound_ctrl:1
	v_add_u32_dpp v67, v67, v67 quad_perm:[2,3,0,1] row_mask:0xf bank_mask:0xf bound_ctrl:1
	v_add_u32_dpp v64, v64, v64 row_half_mirror row_mask:0xf bank_mask:0xf bound_ctrl:1
	v_add_u32_dpp v65, v65, v65 row_half_mirror row_mask:0xf bank_mask:0xf bound_ctrl:1
	v_add_u32_dpp v66, v66, v66 row_half_mirror row_mask:0xf bank_mask:0xf bound_ctrl:1
	v_add_u32_dpp v67, v67, v67 row_half_mirror row_mask:0xf bank_mask:0xf bound_ctrl:1
	v_cvt_f32_i32_e32 v68, v64
	v_cvt_f32_i32_e32 v69, v65
	v_cvt_f32_i32_e32 v70, v66
	v_cvt_f32_i32_e32 v71, v67
	v_pk_mul_f32 v[68:69], v[52:53], v[68:69] op_sel_hi:[0,1]
	v_pk_mul_f32 v[70:71], v[52:53], v[70:71] op_sel_hi:[0,1]
	v_and_b32_e32 v56, s21, v192
	v_lshrrev_b32_e32 v57, 4, v192
	v_and_b32_e32 v57, s21, v57
	v_and_b32_e32 v58, s21, v196
	v_lshrrev_b32_e32 v59, 4, v196
	v_and_b32_e32 v59, s21, v59
	v_and_b32_e32 v60, s21, v200
	v_lshrrev_b32_e32 v61, 4, v200
	v_and_b32_e32 v61, s21, v61
	v_and_b32_e32 v62, s21, v204
	v_lshrrev_b32_e32 v63, 4, v204
	v_and_b32_e32 v63, s21, v63
	v_mov_b32_e32 v64, v85
	v_mov_b32_e32 v65, v85
	v_mov_b32_e32 v66, v85
	v_mov_b32_e32 v67, v85
	v_dot4c_i32_i8_e32 v64, v56, v32
	v_dot4c_i32_i8_e32 v64, v57, v33
	v_dot4c_i32_i8_e32 v65, v58, v32
	v_dot4c_i32_i8_e32 v65, v59, v33
	v_dot4c_i32_i8_e32 v66, v60, v32
	v_dot4c_i32_i8_e32 v66, v61, v33
	v_dot4c_i32_i8_e32 v67, v62, v32
	v_dot4c_i32_i8_e32 v67, v63, v33
	v_and_b32_e32 v56, s21, v193
	v_lshrrev_b32_e32 v57, 4, v193
	v_and_b32_e32 v57, s21, v57
	v_and_b32_e32 v58, s21, v197
	v_lshrrev_b32_e32 v59, 4, v197
	v_and_b32_e32 v59, s21, v59
	v_and_b32_e32 v60, s21, v201
	v_lshrrev_b32_e32 v61, 4, v201
	v_and_b32_e32 v61, s21, v61
	v_and_b32_e32 v62, s21, v205
	v_lshrrev_b32_e32 v63, 4, v205
	v_and_b32_e32 v63, s21, v63
	v_dot4c_i32_i8_e32 v64, v56, v34
	v_dot4c_i32_i8_e32 v64, v57, v35
	v_dot4c_i32_i8_e32 v65, v58, v34
	v_dot4c_i32_i8_e32 v65, v59, v35
	v_dot4c_i32_i8_e32 v66, v60, v34
	v_dot4c_i32_i8_e32 v66, v61, v35
	v_dot4c_i32_i8_e32 v67, v62, v34
	v_dot4c_i32_i8_e32 v67, v63, v35
	v_and_b32_e32 v56, s21, v194
	v_lshrrev_b32_e32 v57, 4, v194
	v_and_b32_e32 v57, s21, v57
	v_and_b32_e32 v58, s21, v198
	v_lshrrev_b32_e32 v59, 4, v198
	v_and_b32_e32 v59, s21, v59
	v_and_b32_e32 v60, s21, v202
	v_lshrrev_b32_e32 v61, 4, v202
	v_and_b32_e32 v61, s21, v61
	v_and_b32_e32 v62, s21, v206
; __device__ __forceinline__ void phase_peer_u(const Params& p, int layer, int xs, int wid0, int wstride, char* smraw) {
;     ...
; #pragma unroll
;     for (int i = 0; i < 16; ++i) {
;       int a = 0;
; #pragma unroll
;       for (int m = 0; m < 4; ++m) {
;         const unsigned dw = q[i][m];
;         a = __builtin_amdgcn_sdot4((int)(dw & 0x0f0f0f0fu), xq[2 * m], a, false);
;         a = __builtin_amdgcn_sdot4((int)((dw >> 4) & 0x0f0f0f0fu), xq[2 * m + 1], a, false);
;       }
;       a -= corr;
;       a += __builtin_amdgcn_update_dpp(0, a, 0xB1, 0xF, 0xF, true);
;       a += __builtin_amdgcn_update_dpp(0, a, 0x4E, 0xF, 0xF, true);
;       a += __builtin_amdgcn_update_dpp(0, a, 0x141, 0xF, 0xF, true);
;       pr[i] = (float)a * sx;
;     }
	v_lshrrev_b32_e32 v63, 4, v206
	v_and_b32_e32 v63, s21, v63
	v_dot4c_i32_i8_e32 v64, v56, v36
	v_dot4c_i32_i8_e32 v64, v57, v37
	v_dot4c_i32_i8_e32 v65, v58, v36
	v_dot4c_i32_i8_e32 v65, v59, v37
	v_dot4c_i32_i8_e32 v66, v60, v36
	v_dot4c_i32_i8_e32 v66, v61, v37
	v_dot4c_i32_i8_e32 v67, v62, v36
	v_dot4c_i32_i8_e32 v67, v63, v37
	v_and_b32_e32 v56, s21, v195
	v_lshrrev_b32_e32 v57, 4, v195
	v_and_b32_e32 v57, s21, v57
	v_and_b32_e32 v58, s21, v199
	v_lshrrev_b32_e32 v59, 4, v199
	v_and_b32_e32 v59, s21, v59
	v_and_b32_e32 v60, s21, v203
	v_lshrrev_b32_e32 v61, 4, v203
	v_and_b32_e32 v61, s21, v61
	v_and_b32_e32 v62, s21, v207
	v_lshrrev_b32_e32 v63, 4, v207
	v_and_b32_e32 v63, s21, v63
	v_dot4c_i32_i8_e32 v64, v56, v38
	v_dot4c_i32_i8_e32 v64, v57, v39
	v_dot4c_i32_i8_e32 v65, v58, v38
	v_dot4c_i32_i8_e32 v65, v59, v39
	v_dot4c_i32_i8_e32 v66, v60, v38
	v_dot4c_i32_i8_e32 v66, v61, v39
	v_dot4c_i32_i8_e32 v67, v62, v38
	v_dot4c_i32_i8_e32 v67, v63, v39
	v_add_u32_dpp v64, v64, v64 quad_perm:[1,0,3,2] row_mask:0xf bank_mask:0xf bound_ctrl:1
	v_add_u32_dpp v65, v65, v65 quad_perm:[1,0,3,2] row_mask:0xf bank_mask:0xf bound_ctrl:1
	v_add_u32_dpp v66, v66, v66 quad_perm:[1,0,3,2] row_mask:0xf bank_mask:0xf bound_ctrl:1
	v_add_u32_dpp v67, v67, v67 quad_perm:[1,0,3,2] row_mask:0xf bank_mask:0xf bound_ctrl:1
	v_add_u32_dpp v64, v64, v64 quad_perm:[2,3,0,1] row_mask:0xf bank_mask:0xf bound_ctrl:1
	v_add_u32_dpp v65, v65, v65 quad_perm:[2,3,0,1] row_mask:0xf bank_mask:0xf bound_ctrl:1
	v_add_u32_dpp v66, v66, v66 quad_perm:[2,3,0,1] row_mask:0xf bank_mask:0xf bound_ctrl:1
	v_add_u32_dpp v67, v67, v67 quad_perm:[2,3,0,1] row_mask:0xf bank_mask:0xf bound_ctrl:1
	v_add_u32_dpp v64, v64, v64 row_half_mirror row_mask:0xf bank_mask:0xf bound_ctrl:1
	v_add_u32_dpp v65, v65, v65 row_half_mirror row_mask:0xf bank_mask:0xf bound_ctrl:1
	v_add_u32_dpp v66, v66, v66 row_half_mirror row_mask:0xf bank_mask:0xf bound_ctrl:1
	v_add_u32_dpp v67, v67, v67 row_half_mirror row_mask:0xf bank_mask:0xf bound_ctrl:1
	v_cvt_f32_i32_e32 v72, v64
	v_cvt_f32_i32_e32 v73, v65
	v_cvt_f32_i32_e32 v74, v66
	v_cvt_f32_i32_e32 v75, v67
	v_pk_mul_f32 v[72:73], v[52:53], v[72:73] op_sel_hi:[0,1]
	v_pk_mul_f32 v[74:75], v[52:53], v[74:75] op_sel_hi:[0,1]
	v_and_b32_e32 v56, s21, v208
	v_lshrrev_b32_e32 v57, 4, v208
	v_and_b32_e32 v57, s21, v57
	v_and_b32_e32 v58, s21, v212
	v_lshrrev_b32_e32 v59, 4, v212
	v_and_b32_e32 v59, s21, v59
	v_and_b32_e32 v60, s21, v216
	v_lshrrev_b32_e32 v61, 4, v216
	v_and_b32_e32 v61, s21, v61
	v_and_b32_e32 v62, s21, v220
	v_lshrrev_b32_e32 v63, 4, v220
	v_and_b32_e32 v63, s21, v63
	v_mov_b32_e32 v64, v85
	v_mov_b32_e32 v65, v85
	v_mov_b32_e32 v66, v85
	v_mov_b32_e32 v67, v85
	v_dot4c_i32_i8_e32 v64, v56, v32
	v_dot4c_i32_i8_e32 v64, v57, v33
	v_dot4c_i32_i8_e32 v65, v58, v32
	v_dot4c_i32_i8_e32 v65, v59, v33
	v_dot4c_i32_i8_e32 v66, v60, v32
	v_dot4c_i32_i8_e32 v66, v61, v33
	v_dot4c_i32_i8_e32 v67, v62, v32
	v_dot4c_i32_i8_e32 v67, v63, v33
	v_and_b32_e32 v56, s21, v209
	v_lshrrev_b32_e32 v57, 4, v209
	v_and_b32_e32 v57, s21, v57
	v_and_b32_e32 v58, s21, v213
	v_lshrrev_b32_e32 v59, 4, v213
	v_and_b32_e32 v59, s21, v59
	v_and_b32_e32 v60, s21, v217
	v_lshrrev_b32_e32 v61, 4, v217
	v_and_b32_e32 v61, s21, v61
	v_and_b32_e32 v62, s21, v221
	v_lshrrev_b32_e32 v63, 4, v221
	v_and_b32_e32 v63, s21, v63
	v_dot4c_i32_i8_e32 v64, v56, v34
	v_dot4c_i32_i8_e32 v64, v57, v35
	v_dot4c_i32_i8_e32 v65, v58, v34
	v_dot4c_i32_i8_e32 v65, v59, v35
	v_dot4c_i32_i8_e32 v66, v60, v34
	v_dot4c_i32_i8_e32 v66, v61, v35
	v_dot4c_i32_i8_e32 v67, v62, v34
	v_dot4c_i32_i8_e32 v67, v63, v35
	v_and_b32_e32 v56, s21, v210
	v_lshrrev_b32_e32 v57, 4, v210
	v_and_b32_e32 v57, s21, v57
	v_and_b32_e32 v58, s21, v214
	v_lshrrev_b32_e32 v59, 4, v214
	v_and_b32_e32 v59, s21, v59
	v_and_b32_e32 v60, s21, v218
	v_lshrrev_b32_e32 v61, 4, v218
	v_and_b32_e32 v61, s21, v61
	v_and_b32_e32 v62, s21, v222
	v_lshrrev_b32_e32 v63, 4, v222
	v_and_b32_e32 v63, s21, v63
	v_dot4c_i32_i8_e32 v64, v56, v36
	v_dot4c_i32_i8_e32 v64, v57, v37
	v_dot4c_i32_i8_e32 v65, v58, v36
	v_dot4c_i32_i8_e32 v65, v59, v37
	v_dot4c_i32_i8_e32 v66, v60, v36
	v_dot4c_i32_i8_e32 v66, v61, v37
	v_dot4c_i32_i8_e32 v67, v62, v36
	v_dot4c_i32_i8_e32 v67, v63, v37
	v_and_b32_e32 v56, s21, v211
	v_lshrrev_b32_e32 v57, 4, v211
	v_and_b32_e32 v57, s21, v57
	v_and_b32_e32 v58, s21, v215
	v_lshrrev_b32_e32 v59, 4, v215
	v_and_b32_e32 v59, s21, v59
	v_and_b32_e32 v60, s21, v219
	v_lshrrev_b32_e32 v61, 4, v219
	v_and_b32_e32 v61, s21, v61
	v_and_b32_e32 v62, s21, v223
	v_lshrrev_b32_e32 v63, 4, v223
	v_and_b32_e32 v63, s21, v63
	v_dot4c_i32_i8_e32 v64, v56, v38
	v_dot4c_i32_i8_e32 v64, v57, v39
	v_dot4c_i32_i8_e32 v65, v58, v38
	v_dot4c_i32_i8_e32 v65, v59, v39
	v_dot4c_i32_i8_e32 v66, v60, v38
	v_dot4c_i32_i8_e32 v66, v61, v39
	v_dot4c_i32_i8_e32 v67, v62, v38
	v_dot4c_i32_i8_e32 v67, v63, v39
	v_add_u32_dpp v64, v64, v64 quad_perm:[1,0,3,2] row_mask:0xf bank_mask:0xf bound_ctrl:1
	v_add_u32_dpp v65, v65, v65 quad_perm:[1,0,3,2] row_mask:0xf bank_mask:0xf bound_ctrl:1
	v_add_u32_dpp v66, v66, v66 quad_perm:[1,0,3,2] row_mask:0xf bank_mask:0xf bound_ctrl:1
	v_add_u32_dpp v67, v67, v67 quad_perm:[1,0,3,2] row_mask:0xf bank_mask:0xf bound_ctrl:1
	v_add_u32_dpp v64, v64, v64 quad_perm:[2,3,0,1] row_mask:0xf bank_mask:0xf bound_ctrl:1
; __device__ __forceinline__ void phase_peer_u(const Params& p, int layer, int xs, int wid0, int wstride, char* smraw) {
;     ...
; #pragma unroll
;     for (int i = 0; i < 16; ++i) {
;       int a = 0;
; #pragma unroll
;       for (int m = 0; m < 4; ++m) {
;         const unsigned dw = q[i][m];
;         a = __builtin_amdgcn_sdot4((int)(dw & 0x0f0f0f0fu), xq[2 * m], a, false);
;         a = __builtin_amdgcn_sdot4((int)((dw >> 4) & 0x0f0f0f0fu), xq[2 * m + 1], a, false);
;       }
;       a -= corr;
;       a += __builtin_amdgcn_update_dpp(0, a, 0xB1, 0xF, 0xF, true);
;       a += __builtin_amdgcn_update_dpp(0, a, 0x4E, 0xF, 0xF, true);
;       a += __builtin_amdgcn_update_dpp(0, a, 0x141, 0xF, 0xF, true);
;       pr[i] = (float)a * sx;
;     }
;     if (j == 0) {
;       f32x4* dst = (f32x4*)((char*)p.actp + ((unsigned)t * 4096u + (unsigned)(sl * 512 + g * 64)));
; #pragma unroll
;       for (int q4 = 0; q4 < 4; ++q4) dst[q4] = f32x4{pr[q4 * 4], pr[q4 * 4 + 1], pr[q4 * 4 + 2], pr[q4 * 4 + 3]};
;     }
	v_add_u32_dpp v65, v65, v65 quad_perm:[2,3,0,1] row_mask:0xf bank_mask:0xf bound_ctrl:1
	v_add_u32_dpp v66, v66, v66 quad_perm:[2,3,0,1] row_mask:0xf bank_mask:0xf bound_ctrl:1
	v_add_u32_dpp v67, v67, v67 quad_perm:[2,3,0,1] row_mask:0xf bank_mask:0xf bound_ctrl:1
	v_add_u32_dpp v64, v64, v64 row_half_mirror row_mask:0xf bank_mask:0xf bound_ctrl:1
	v_add_u32_dpp v65, v65, v65 row_half_mirror row_mask:0xf bank_mask:0xf bound_ctrl:1
	v_add_u32_dpp v66, v66, v66 row_half_mirror row_mask:0xf bank_mask:0xf bound_ctrl:1
	v_add_u32_dpp v67, v67, v67 row_half_mirror row_mask:0xf bank_mask:0xf bound_ctrl:1
	v_cvt_f32_i32_e32 v76, v64
	v_cvt_f32_i32_e32 v77, v65
	v_cvt_f32_i32_e32 v78, v66
	v_cvt_f32_i32_e32 v79, v67
	v_pk_mul_f32 v[76:77], v[52:53], v[76:77] op_sel_hi:[0,1]
	v_pk_mul_f32 v[78:79], v[52:53], v[78:79] op_sel_hi:[0,1]
	v_and_b32_e32 v56, s21, v224
	v_lshrrev_b32_e32 v57, 4, v224
	v_and_b32_e32 v57, s21, v57
	v_and_b32_e32 v58, s21, v228
	v_lshrrev_b32_e32 v59, 4, v228
	v_and_b32_e32 v59, s21, v59
	v_and_b32_e32 v60, s21, v232
	v_lshrrev_b32_e32 v61, 4, v232
	v_and_b32_e32 v61, s21, v61
	v_and_b32_e32 v62, s21, v236
	v_lshrrev_b32_e32 v63, 4, v236
	v_and_b32_e32 v63, s21, v63
	v_mov_b32_e32 v64, v85
	v_mov_b32_e32 v65, v85
	v_mov_b32_e32 v66, v85
	v_mov_b32_e32 v67, v85
	v_dot4c_i32_i8_e32 v64, v56, v32
	v_dot4c_i32_i8_e32 v64, v57, v33
	v_dot4c_i32_i8_e32 v65, v58, v32
	v_dot4c_i32_i8_e32 v65, v59, v33
	v_dot4c_i32_i8_e32 v66, v60, v32
	v_dot4c_i32_i8_e32 v66, v61, v33
	v_dot4c_i32_i8_e32 v67, v62, v32
	v_dot4c_i32_i8_e32 v67, v63, v33
	v_and_b32_e32 v56, s21, v225
	v_lshrrev_b32_e32 v57, 4, v225
	v_and_b32_e32 v57, s21, v57
	v_and_b32_e32 v58, s21, v229
	v_lshrrev_b32_e32 v59, 4, v229
	v_and_b32_e32 v59, s21, v59
	v_and_b32_e32 v60, s21, v233
	v_lshrrev_b32_e32 v61, 4, v233
	v_and_b32_e32 v61, s21, v61
	v_and_b32_e32 v62, s21, v237
	v_lshrrev_b32_e32 v63, 4, v237
	v_and_b32_e32 v63, s21, v63
	v_dot4c_i32_i8_e32 v64, v56, v34
	v_dot4c_i32_i8_e32 v64, v57, v35
	v_dot4c_i32_i8_e32 v65, v58, v34
	v_dot4c_i32_i8_e32 v65, v59, v35
	v_dot4c_i32_i8_e32 v66, v60, v34
	v_dot4c_i32_i8_e32 v66, v61, v35
	v_dot4c_i32_i8_e32 v67, v62, v34
	v_dot4c_i32_i8_e32 v67, v63, v35
	v_and_b32_e32 v56, s21, v226
	v_lshrrev_b32_e32 v57, 4, v226
	v_and_b32_e32 v57, s21, v57
	v_and_b32_e32 v58, s21, v230
	v_lshrrev_b32_e32 v59, 4, v230
	v_and_b32_e32 v59, s21, v59
	v_and_b32_e32 v60, s21, v234
	v_lshrrev_b32_e32 v61, 4, v234
	v_and_b32_e32 v61, s21, v61
	v_and_b32_e32 v62, s21, v238
	v_lshrrev_b32_e32 v63, 4, v238
	v_and_b32_e32 v63, s21, v63
	v_dot4c_i32_i8_e32 v64, v56, v36
	v_dot4c_i32_i8_e32 v64, v57, v37
	v_dot4c_i32_i8_e32 v65, v58, v36
	v_dot4c_i32_i8_e32 v65, v59, v37
	v_dot4c_i32_i8_e32 v66, v60, v36
	v_dot4c_i32_i8_e32 v66, v61, v37
	v_dot4c_i32_i8_e32 v67, v62, v36
	v_dot4c_i32_i8_e32 v67, v63, v37
	v_and_b32_e32 v56, s21, v227
	v_lshrrev_b32_e32 v57, 4, v227
	v_and_b32_e32 v57, s21, v57
	v_and_b32_e32 v58, s21, v231
	v_lshrrev_b32_e32 v59, 4, v231
	v_and_b32_e32 v59, s21, v59
	v_and_b32_e32 v60, s21, v235
	v_lshrrev_b32_e32 v61, 4, v235
	v_and_b32_e32 v61, s21, v61
	v_and_b32_e32 v62, s21, v239
	v_lshrrev_b32_e32 v63, 4, v239
	v_and_b32_e32 v63, s21, v63
	v_dot4c_i32_i8_e32 v64, v56, v38
	v_dot4c_i32_i8_e32 v64, v57, v39
	v_dot4c_i32_i8_e32 v65, v58, v38
	v_dot4c_i32_i8_e32 v65, v59, v39
	v_dot4c_i32_i8_e32 v66, v60, v38
	v_dot4c_i32_i8_e32 v66, v61, v39
	v_dot4c_i32_i8_e32 v67, v62, v38
	v_dot4c_i32_i8_e32 v67, v63, v39
	v_add_u32_dpp v64, v64, v64 quad_perm:[1,0,3,2] row_mask:0xf bank_mask:0xf bound_ctrl:1
	v_add_u32_dpp v65, v65, v65 quad_perm:[1,0,3,2] row_mask:0xf bank_mask:0xf bound_ctrl:1
	v_add_u32_dpp v66, v66, v66 quad_perm:[1,0,3,2] row_mask:0xf bank_mask:0xf bound_ctrl:1
	v_add_u32_dpp v67, v67, v67 quad_perm:[1,0,3,2] row_mask:0xf bank_mask:0xf bound_ctrl:1
	v_add_u32_dpp v64, v64, v64 quad_perm:[2,3,0,1] row_mask:0xf bank_mask:0xf bound_ctrl:1
	v_add_u32_dpp v65, v65, v65 quad_perm:[2,3,0,1] row_mask:0xf bank_mask:0xf bound_ctrl:1
	v_add_u32_dpp v66, v66, v66 quad_perm:[2,3,0,1] row_mask:0xf bank_mask:0xf bound_ctrl:1
	v_add_u32_dpp v67, v67, v67 quad_perm:[2,3,0,1] row_mask:0xf bank_mask:0xf bound_ctrl:1
	v_add_u32_dpp v64, v64, v64 row_half_mirror row_mask:0xf bank_mask:0xf bound_ctrl:1
	v_add_u32_dpp v65, v65, v65 row_half_mirror row_mask:0xf bank_mask:0xf bound_ctrl:1
	v_add_u32_dpp v66, v66, v66 row_half_mirror row_mask:0xf bank_mask:0xf bound_ctrl:1
	v_add_u32_dpp v67, v67, v67 row_half_mirror row_mask:0xf bank_mask:0xf bound_ctrl:1
	v_cvt_f32_i32_e32 v80, v64
	v_cvt_f32_i32_e32 v81, v65
	v_cvt_f32_i32_e32 v82, v66
	v_cvt_f32_i32_e32 v83, v67
	v_pk_mul_f32 v[80:81], v[52:53], v[80:81] op_sel_hi:[0,1]
	v_pk_mul_f32 v[82:83], v[52:53], v[82:83] op_sel_hi:[0,1]
	s_lshl_b32 s70, s60, 1
	s_add_u32 s70, s70, s28
	s_lshl_b32 s70, s70, 12
	s_add_u32 s70, s70, s68
	s_mov_b64 s[74:75], exec
	s_and_b64 exec, exec, s[72:73]
	v_add_u32_e32 v9, s70, v5
	global_store_dwordx4 v9, v[68:71], s[64:65]
	global_store_dwordx4 v9, v[72:75], s[64:65] offset:16
	global_store_dwordx4 v9, v[76:79], s[64:65] offset:32
	global_store_dwordx4 v9, v[80:83], s[64:65] offset:48
	s_mov_b64 exec, s[74:75]
	s_mov_b32 s60, s62
	s_cmp_lt_u32 s60, s61
	s_cbranch_scc1 .Lmy_pu0_bodyA
